# in-proj unit deal: q column tiles moved to the odd XCDs in exchange for four u tiles (instead of the k tiles)
# speedup vs baseline: 1.0097x; 1.0028x over previous
.LBB0_176:
	s_cmp_lt_i32 s26, 3
	s_cselect_b64 s[6:7], -1, 0
	s_and_b64 s[10:11], s[6:7], s[4:5]
	s_andn2_b64 vcc, exec, s[10:11]
	s_cbranch_vccnz .LBB0_291
	s_cmpk_lt_i32 s2, 0x300
	s_cselect_b64 s[4:5], -1, 0
	s_cmpk_gt_i32 s2, 0x2ff
	s_mov_b64 s[12:13], s[24:25]
	v_readfirstlane_b32 s22, v0
	s_cbranch_scc1 .LBB0_179
	s_ashr_i32 s6, s2, 31
	s_lshr_b32 s6, s6, 29
	s_add_i32 s6, s2, s6
	s_ashr_i32 s7, s6, 3
	s_and_b32 s6, s6, -8
	s_sub_i32 s6, s2, s6
	s_cmp_lt_i32 s6, 0
	s_movk_i32 s8, 0x61
	s_cselect_b32 s8, s8, 0x60
	s_mul_i32 s6, s6, s8
	s_add_i32 s6, s6, s7
	s_mul_hi_i32 s7, s6, 0x2aaaaaab
	s_lshr_b32 s8, s7, 31
	s_ashr_i32 s7, s7, 5
	s_add_i32 s7, s7, s8
	s_lshl_b32 s8, s7, 3
	s_mulk_i32 s7, 0xc0
	s_sub_i32 s7, s6, s7
	s_sext_i32_i16 s6, s7
	s_bfe_u32 s6, s6, 0x3001c
	s_add_i32 s6, s7, s6
	s_sext_i32_i16 s9, s6
	s_and_b32 s6, s6, 0xfff8
	s_sub_i32 s6, s7, s6
	s_sext_i32_i16 s6, s6
	s_add_i32 s6, s8, s6
	s_ashr_i32 s8, s9, 3
	s_add_i32 s9, s8, 4
	s_cmpk_gt_i32 s7, 0x5f
	s_cselect_b32 s62, s9, s8
	s_add_i32 s7, s62, 16
	s_sub_i32 s8, s62, 16
	s_sub_i32 s9, s62, 0
	s_cmp_lt_u32 s9, 4
	s_cselect_b32 s7, s7, s62
	s_sub_i32 s9, s62, 16
	s_cmp_lt_u32 s9, 4
	s_cselect_b32 s62, s8, s7

.LBB0_185:
	s_add_i32 s83, s83, 1
	s_mul_i32 s4, s83, s84
	s_mul_hi_u32 s5, s83, s3
	s_add_i32 s5, s5, s4
	s_mul_i32 s4, s83, s3
	s_add_u32 s58, s4, s2
	s_addc_u32 s59, s5, s85
	v_mov_b64_e32 v[2:3], 0x300
	v_cmp_lt_i64_e64 s[4:5], s[58:59], v[2:3]
	v_mov_b64_e32 v[2:3], 0x2ff
	v_cmp_gt_i64_e32 vcc, s[58:59], v[2:3]
	s_cbranch_vccnz .LBB0_187
	s_ashr_i32 s7, s58, 31
	s_lshr_b32 s7, s7, 29
	s_add_i32 s7, s58, s7
	s_ashr_i32 s54, s7, 3
	s_and_b32 s7, s7, -8
	s_sub_i32 s7, s58, s7
	s_cmp_lt_i32 s7, 0
	s_cselect_b32 s55, s88, 0x60
	s_mul_i32 s7, s7, s55
	s_add_i32 s7, s7, s54
	s_mul_hi_i32 s54, s7, 0x2aaaaaab
	s_lshr_b32 s55, s54, 31
	s_ashr_i32 s54, s54, 5
	s_add_i32 s54, s54, s55
	s_lshl_b32 s55, s54, 3
	s_sub_i32 s56, 32, s55
	s_min_i32 s56, s56, 8
	s_abs_i32 s57, s56
	v_cvt_f32_u32_e32 v2, s57
	s_sub_i32 s59, 0, s57
	s_mulk_i32 s54, 0xc0
	s_sub_i32 s7, s7, s54
	v_rcp_iflag_f32_e32 v2, v2
	s_abs_i32 s54, s7
	s_xor_b32 s58, s7, s56
	s_ashr_i32 s58, s58, 31
	v_mul_f32_e32 v2, 0x4f7ffffe, v2
	v_cvt_u32_f32_e32 v2, v2
	s_nop 0
	v_readfirstlane_b32 s60, v2
	s_mul_i32 s59, s59, s60
	s_mul_hi_u32 s59, s60, s59
	s_add_i32 s60, s60, s59
	s_mul_hi_u32 s59, s54, s60
	s_mul_i32 s60, s59, s57
	s_sub_i32 s54, s54, s60
	s_add_i32 s61, s59, 1
	s_sub_i32 s60, s54, s57
	s_cmp_ge_u32 s54, s57
	s_cselect_b32 s59, s61, s59
	s_cselect_b32 s54, s60, s54
	s_add_i32 s60, s59, 1
	s_cmp_ge_u32 s54, s57
	s_cselect_b32 s54, s60, s59
	s_xor_b32 s54, s54, s58
	s_sub_i32 s57, s54, s58
	s_mul_i32 s54, s57, s56
	s_sub_i32 s7, s7, s54
	s_add_i32 s54, s55, s7
	s_add_i32 s7, s57, 4
	s_cmp_gt_i32 s57, 11
	s_cselect_b32 s56, s7, s57
	s_add_i32 s57, s56, 16
	s_sub_i32 s58, s56, 16
	s_sub_i32 s59, s56, 0
	s_cmp_lt_u32 s59, 4
	s_cselect_b32 s57, s57, s56
	s_sub_i32 s59, s56, 16
	s_cmp_lt_u32 s59, 4
	s_cselect_b32 s56, s58, s57
